# combo5_nomax + attention closing barrier moved one P.V slot earlier (tail MFMA+4 exps after the barrier)
# baseline (speedup 1.0000x reference)
.LBB0_486:
	s_waitcnt lgkmcnt(14)
	v_mfma_f32_32x32x16_bf16 v[18:33], v[138:141], v[178:181], v[18:33]
	v_exp_f32_e32 v98, v98
	v_exp_f32_e32 v99, v99
	v_exp_f32_e32 v100, v100
	v_exp_f32_e32 v101, v101
	s_waitcnt lgkmcnt(12)
	v_mfma_f32_32x32x16_bf16 v[2:17], v[138:141], v[174:177], v[2:17]
	v_exp_f32_e32 v102, v102
	v_exp_f32_e32 v103, v103
	v_exp_f32_e32 v104, v104
	v_exp_f32_e32 v105, v105
	v_add_u32_e32 v78, s14, v202
	ds_read_b128 v[62:65], v78
	ds_read_b128 v[174:177], v78 offset:512
	s_waitcnt lgkmcnt(12)
	v_mfma_f32_32x32x16_bf16 v[18:33], v[130:133], v[66:69], v[18:33]
	v_exp_f32_e32 v106, v106
	v_exp_f32_e32 v107, v107
	v_exp_f32_e32 v108, v108
	v_exp_f32_e32 v109, v109
	ds_read_b128 v[178:181], v78 offset:2048
	ds_read_b128 v[170:173], v78 offset:2560
	s_waitcnt lgkmcnt(12)
	v_mfma_f32_32x32x16_bf16 v[2:17], v[130:133], v[70:73], v[2:17]
	v_exp_f32_e32 v110, v110
	v_exp_f32_e32 v111, v111
	v_exp_f32_e32 v112, v112
	v_exp_f32_e32 v113, v113
	ds_read_b128 v[166:169], v78 offset:4096
	ds_read_b128 v[162:165], v78 offset:4608
	s_waitcnt lgkmcnt(12)
	v_mfma_f32_32x32x16_bf16 v[18:33], v[122:125], v[74:77], v[18:33]
	v_exp_f32_e32 v82, v82
	v_exp_f32_e32 v83, v83
	v_exp_f32_e32 v84, v84
	v_exp_f32_e32 v85, v85
	ds_read_b128 v[158:161], v78 offset:6144
	ds_read_b128 v[154:157], v78 offset:6656
	s_waitcnt lgkmcnt(12)
	v_mfma_f32_32x32x16_bf16 v[2:17], v[122:125], v[50:53], v[2:17]
	v_exp_f32_e32 v86, v86
	v_exp_f32_e32 v87, v87
	v_exp_f32_e32 v88, v88
	v_exp_f32_e32 v89, v89
	s_waitcnt lgkmcnt(10)
	v_mfma_f32_32x32x16_bf16 v[18:33], v[114:117], v[54:57], v[18:33]
	v_exp_f32_e32 v90, v90
	v_exp_f32_e32 v91, v91
	v_exp_f32_e32 v92, v92
	v_exp_f32_e32 v93, v93
	s_waitcnt vmcnt(2) lgkmcnt(0)
	s_barrier
	s_waitcnt lgkmcnt(8)
	v_mfma_f32_32x32x16_bf16 v[2:17], v[114:117], v[58:61], v[2:17]
	v_exp_f32_e32 v94, v94
	v_exp_f32_e32 v95, v95
	v_exp_f32_e32 v96, v96
	v_exp_f32_e32 v97, v97
	s_andn2_b64 vcc, exec, s[4:5]
	v_add_u32_e32 v191, s18, v204
	s_cbranch_vccnz .LBB0_488
	s_waitcnt lgkmcnt(0)
	ds_read_b128 v[50:53], v191 offset:49248
	ds_read_b128 v[54:57], v191 offset:49216
	ds_read_b128 v[58:61], v191 offset:49184
	ds_read_b128 v[66:69], v191 offset:49152
	s_waitcnt lgkmcnt(3)
	v_pk_mul_f32 v[30:31], v[30:31], v[50:51]
	s_waitcnt lgkmcnt(2)
	v_pk_mul_f32 v[26:27], v[26:27], v[54:55]
	s_waitcnt lgkmcnt(1)
	v_pk_mul_f32 v[22:23], v[22:23], v[58:59]
	v_pk_mul_f32 v[32:33], v[32:33], v[52:53]
	v_pk_mul_f32 v[28:29], v[28:29], v[56:57]
	v_pk_mul_f32 v[24:25], v[24:25], v[60:61]
	s_waitcnt lgkmcnt(0)
	v_pk_mul_f32 v[20:21], v[20:21], v[68:69]
	v_pk_mul_f32 v[18:19], v[18:19], v[66:67]
	v_pk_mul_f32 v[14:15], v[14:15], v[50:51]
	v_pk_mul_f32 v[10:11], v[10:11], v[54:55]
	v_pk_mul_f32 v[6:7], v[6:7], v[58:59]
	v_pk_mul_f32 v[16:17], v[16:17], v[52:53]
	v_pk_mul_f32 v[12:13], v[12:13], v[56:57]
	v_pk_mul_f32 v[8:9], v[8:9], v[60:61]
	v_pk_mul_f32 v[4:5], v[4:5], v[68:69]
	v_pk_mul_f32 v[2:3], v[2:3], v[66:67]

.LBB0_489:
	s_waitcnt lgkmcnt(14)
	v_mfma_f32_32x32x16_bf16 v[18:33], v[138:141], v[150:153], v[18:33]
	v_exp_f32_e32 v66, v66
	v_exp_f32_e32 v67, v67
	v_exp_f32_e32 v68, v68
	v_exp_f32_e32 v69, v69
	s_waitcnt lgkmcnt(12)
	v_mfma_f32_32x32x16_bf16 v[2:17], v[138:141], v[146:149], v[2:17]
	v_exp_f32_e32 v70, v70
	v_exp_f32_e32 v71, v71
	v_exp_f32_e32 v72, v72
	v_exp_f32_e32 v73, v73
	v_add_u32_e32 v94, s50, v202
	ds_read_b128 v[174:177], v94
	ds_read_b128 v[170:173], v94 offset:512
	s_waitcnt lgkmcnt(12)
	v_mfma_f32_32x32x16_bf16 v[18:33], v[130:133], v[98:101], v[18:33]
	v_exp_f32_e32 v74, v74
	v_exp_f32_e32 v75, v75
	v_exp_f32_e32 v76, v76
	v_exp_f32_e32 v77, v77
	ds_read_b128 v[166:169], v94 offset:2048
	ds_read_b128 v[162:165], v94 offset:2560
	s_waitcnt lgkmcnt(12)
	v_mfma_f32_32x32x16_bf16 v[2:17], v[130:133], v[102:105], v[2:17]
	v_exp_f32_e32 v78, v78
	v_exp_f32_e32 v79, v79
	v_exp_f32_e32 v80, v80
	v_exp_f32_e32 v81, v81
	ds_read_b128 v[158:161], v94 offset:4096
	ds_read_b128 v[154:157], v94 offset:4608
	s_waitcnt lgkmcnt(12)
	v_mfma_f32_32x32x16_bf16 v[18:33], v[122:125], v[106:109], v[18:33]
	v_exp_f32_e32 v50, v50
	v_exp_f32_e32 v51, v51
	v_exp_f32_e32 v52, v52
	v_exp_f32_e32 v53, v53
	ds_read_b128 v[150:153], v94 offset:6144
	ds_read_b128 v[146:149], v94 offset:6656
	s_waitcnt lgkmcnt(12)
	v_mfma_f32_32x32x16_bf16 v[2:17], v[122:125], v[82:85], v[2:17]
	v_exp_f32_e32 v54, v54
	v_exp_f32_e32 v55, v55
	v_exp_f32_e32 v56, v56
	v_exp_f32_e32 v57, v57
	s_waitcnt lgkmcnt(10)
	v_mfma_f32_32x32x16_bf16 v[18:33], v[114:117], v[86:89], v[18:33]
	v_exp_f32_e32 v58, v58
	v_exp_f32_e32 v59, v59
	v_exp_f32_e32 v60, v60
	v_exp_f32_e32 v61, v61
	s_waitcnt vmcnt(2) lgkmcnt(0)
	s_barrier
	s_waitcnt lgkmcnt(8)
	v_mfma_f32_32x32x16_bf16 v[2:17], v[114:117], v[90:93], v[2:17]
	v_exp_f32_e32 v62, v62
	v_exp_f32_e32 v63, v63
	v_exp_f32_e32 v64, v64
	v_exp_f32_e32 v65, v65
	s_andn2_b64 vcc, exec, s[4:5]
	s_cbranch_vccnz .LBB0_491
	s_waitcnt lgkmcnt(0)
	ds_read_b128 v[82:85], v191 offset:49248
	ds_read_b128 v[86:89], v191 offset:49216
	ds_read_b128 v[90:93], v191 offset:49152
	ds_read_b128 v[94:97], v191 offset:49184
	s_waitcnt lgkmcnt(3)
	v_pk_mul_f32 v[32:33], v[32:33], v[84:85]
	v_pk_mul_f32 v[30:31], v[30:31], v[82:83]
	s_waitcnt lgkmcnt(2)
	v_pk_mul_f32 v[28:29], v[28:29], v[88:89]
	v_pk_mul_f32 v[26:27], v[26:27], v[86:87]
	s_waitcnt lgkmcnt(0)
	v_pk_mul_f32 v[24:25], v[24:25], v[96:97]
	v_pk_mul_f32 v[22:23], v[22:23], v[94:95]
	v_pk_mul_f32 v[20:21], v[20:21], v[92:93]
	v_pk_mul_f32 v[18:19], v[18:19], v[90:91]
	v_pk_mul_f32 v[16:17], v[16:17], v[84:85]
	v_pk_mul_f32 v[14:15], v[14:15], v[82:83]
	v_pk_mul_f32 v[12:13], v[12:13], v[88:89]
	v_pk_mul_f32 v[10:11], v[10:11], v[86:87]
	v_pk_mul_f32 v[8:9], v[8:9], v[96:97]
	v_pk_mul_f32 v[6:7], v[6:7], v[94:95]
	v_pk_mul_f32 v[4:5], v[4:5], v[92:93]
	v_pk_mul_f32 v[2:3], v[2:3], v[90:91]
